# grid barrier: every workgroup issues an extra asynchronous L2 write-back at arrival as a pre-cleaning hint (required write-back kept); on top of v82
# baseline (speedup 1.0000x reference)
.LBB0_837:
	v_readlane_b32 s2, v254, 9
	v_readlane_b32 s3, v254, 10
	v_mov_b32_e32 v1, 1
	v_sub_u32_e32 v4, 0, v2
	s_nop 2
	buffer_wbl2 sc1
	global_atomic_add v3, v141, v1, s[2:3] sc0
	v_cvt_f32_u32_e32 v1, v2
	v_rcp_iflag_f32_e32 v1, v1
	s_nop 0
	v_mul_f32_e32 v1, 0x4f7ffffe, v1
	v_cvt_u32_f32_e32 v1, v1
	v_mul_lo_u32 v4, v4, v1
	v_mul_hi_u32 v4, v1, v4
	v_add_u32_e32 v1, v1, v4
	s_waitcnt vmcnt(0)
	v_mul_hi_u32 v1, v3, v1
	v_mul_lo_u32 v4, v1, v2
	v_sub_u32_e32 v4, v3, v4
	v_add_u32_e32 v5, 1, v1
	v_cmp_ge_u32_e32 vcc, v4, v2
	v_add_u32_e32 v3, 1, v3
	s_nop 0
	v_cndmask_b32_e32 v1, v1, v5, vcc
	v_sub_u32_e32 v5, v4, v2
	v_cndmask_b32_e32 v4, v4, v5, vcc
	v_add_u32_e32 v5, 1, v1
	v_cmp_ge_u32_e32 vcc, v4, v2
	s_nop 1
	v_cndmask_b32_e32 v1, v1, v5, vcc
	v_mul_lo_u32 v4, v2, v1
	v_add_u32_e32 v2, v4, v2
	v_cmp_ne_u32_e32 vcc, v3, v2
	s_and_saveexec_b64 s[6:7], vcc
	s_xor_b64 s[6:7], exec, s[6:7]
	s_cbranch_execz .LBB0_851
	v_readlane_b32 s2, v254, 11
	v_readlane_b32 s3, v254, 12
	s_waitcnt lgkmcnt(0)
	s_nop 3
	buffer_inv sc1
	global_load_dword v0, v141, s[2:3] sc1
	s_waitcnt vmcnt(0)
	v_cmp_eq_u32_e32 vcc, v0, v1
	s_and_saveexec_b64 s[8:9], vcc
	s_cbranch_execz .LBB0_850
	s_mov_b32 s4, 1
	s_mov_b64 s[10:11], 0
	s_branch .LBB0_841
